# E29: gemm_phase prologues issue all 14 LDS-DMA loads (K-tiles 0 and 1) before the first wait/barrier (vmcnt(2)->vmcnt(8)); on E28
# baseline (speedup 1.0000x reference)
.LBB0_291:
	s_and_b32 s22, s18, 3
	s_lshl_b32 s46, s19, 6
	s_lshl_b32 s19, s19, 13
	s_lshl_b32 s26, s18, 5
	s_lshl_b32 s22, s22, 12
	s_add_u32 s25, s8, 0x47300000
	s_addc_u32 s30, s9, 0
	s_add_i32 s31, s2, 0x18000
	s_or_b32 s8, s95, 0x80
	s_mov_b32 s42, s62
	s_mov_b32 s43, s63
	s_mov_b32 m0, s31
	s_add_i32 s33, s2, 0x1a000
	buffer_load_dwordx4 v133, s[40:43], s8 offen lds
	s_mov_b32 m0, s33
	s_add_i32 s36, s2, 0x8000
	buffer_load_dwordx4 v135, s[40:43], s8 offen lds
	s_or_b32 s8, s94, 0x80
	s_mov_b32 m0, s36
	s_add_i32 s37, s2, 0xa000
	buffer_load_dwordx4 v132, s[60:63], s8 offen lds
	s_mov_b32 m0, s37
	s_add_i32 s68, s2, 0x1c000
	buffer_load_dwordx4 v134, s[60:63], s8 offen lds
	s_or_b32 s8, s95, 0x80080
	s_mov_b32 m0, s68
	s_add_i32 s69, s2, 0x1e000
	buffer_load_dwordx4 v133, s[40:43], s8 offen lds
	s_mov_b32 m0, s69
	s_add_i32 s72, s2, 0xc000
	buffer_load_dwordx4 v135, s[40:43], s8 offen lds
	s_mov_b64 vcc, s[44:45]
	s_cbranch_vccz .Lgk_p1_0
	s_barrier
.Lgk_p1_0:
	s_waitcnt vmcnt(8)
	s_barrier
	s_cmpk_lt_u32 s12, 0x100
	s_cselect_b64 s[48:49], -1, 0
	s_or_b32 s8, s46, 16
	s_ashr_i32 s9, s8, 31
	s_lshl_b64 s[66:67], s[8:9], 7
	s_or_b32 s8, s46, 32
	v_and_b32_e32 v3, 15, v2
	v_lshrrev_b32_e32 v4, 1, v2
	s_ashr_i32 s9, s8, 31
	v_and_b32_e32 v4, 24, v4
	v_lshlrev_b32_e32 v5, 6, v3
	v_lshlrev_b32_e32 v2, 2, v2
	s_lshl_b64 s[70:71], s[8:9], 7
	s_or_b32 s8, s46, 48
	v_lshl_or_b32 v6, v4, 1, v5
	v_and_b32_e32 v2, 32, v2
	s_ashr_i32 s47, s46, 31
	s_ashr_i32 s9, s8, 31
	v_bitop3_b32 v7, v6, s19, v2 bitop3:0xde
	s_bfe_u32 s73, s18, 0x10001
	s_and_b32 s19, s26, 32
	s_lshl_b64 s[64:65], s[46:47], 7
	s_add_i32 s47, s2, 0xe000
	s_lshl_b64 s[26:27], s[8:9], 7
	v_bitop3_b32 v6, v6, s22, v2 bitop3:0xde
	s_add_u32 s22, s64, 0x4000
	s_addc_u32 s82, s65, 0
	s_add_u32 s12, s64, 0x4800
	s_addc_u32 s83, s65, 0
	s_add_u32 s84, s64, 0x5000
	s_waitcnt vmcnt(6)
	s_addc_u32 s85, s65, 0
	v_readlane_b32 s8, v252, 58
	v_or_b32_e32 v2, v4, v5
	s_add_u32 s86, s64, 0x5800
	v_lshlrev_b32_e32 v146, 3, v3
	v_readlane_b32 s9, v252, 59
	v_add_u32_e32 v3, 0, v6
	s_addc_u32 s87, s65, 0
	v_lshl_add_u64 v[130:131], s[8:9], 0, v[146:147]
	s_mov_b32 s18, 0
	v_add_u32_e32 v136, 0x10000, v3
	v_add_u32_e32 v137, 0x14000, v3
	v_add_u32_e32 v138, 0, v7
	v_add_u32_e32 v139, 0x18000, v3
	v_add_u32_e32 v140, 0x1c000, v3
	s_lshl_b32 s88, s19, 1
	v_lshlrev_b32_e32 v141, 1, v2
	s_barrier
	s_branch .LBB0_294

.LBB0_574:
	s_lshl_b32 s12, s12, 5
	s_and_b32 s33, s12, 0x60
	s_lshl_b32 s31, s13, 6
	s_lshl_b32 s13, s13, 13
	s_lshl_b32 s12, s33, 7
	v_readlane_b32 s21, v255, 48
	s_add_u32 s34, s8, s21
	s_addc_u32 s35, s9, 0
	s_add_i32 s36, s14, 0x18000
	s_mov_b32 s46, s62
	s_mov_b32 s47, s63
	s_mov_b32 m0, s36
	v_readlane_b32 s8, v254, 53
	s_add_i32 s37, s14, 0x1a000
	s_add_i32 s48, s14, 0x8000
	s_add_i32 s49, s14, 0xa000
	s_nop 0
	buffer_load_dwordx4 v137, s[44:47], s8 offen lds
	s_mov_b32 m0, s37
	s_add_i32 s66, s14, 0x1c000
	buffer_load_dwordx4 v139, s[44:47], s8 offen lds
	s_mov_b32 m0, s48
	v_readlane_b32 s8, v254, 55
	s_add_i32 s67, s14, 0x1e000
	v_bfe_u32 v4, v2, 4, 2
	v_and_b32_e32 v3, 15, v2
	v_lshlrev_b32_e32 v5, 4, v4
	v_lshlrev_b32_e32 v2, 2, v2
	buffer_load_dwordx4 v136, s[60:63], s8 offen lds
	s_mov_b32 m0, s49
	v_lshl_or_b32 v5, v3, 6, v5
	buffer_load_dwordx4 v138, s[60:63], s8 offen lds
	s_mov_b32 m0, s66
	v_readlane_b32 s8, v254, 57
	v_and_b32_e32 v2, 32, v2
	v_bitop3_b32 v6, v5, s13, v2 bitop3:0xde
	v_bitop3_b32 v5, v5, s12, v2 bitop3:0xde
	s_add_i32 s68, s14, 0xc000
	v_lshlrev_b32_e32 v2, 11, v3
	buffer_load_dwordx4 v137, s[44:47], s8 offen lds
	s_mov_b32 m0, s67
	s_cmpk_lt_u32 s2, 0x100
	buffer_load_dwordx4 v139, s[44:47], s8 offen lds
	s_mov_b64 vcc, s[38:39]
	s_cbranch_vccz .Lgk_p1_1
	s_barrier
.Lgk_p1_1:
	s_waitcnt vmcnt(8)
	s_barrier
	s_waitcnt vmcnt(6)
	v_lshl_or_b32 v2, v4, 3, v2
	v_lshlrev_b32_e32 v146, 3, v3
	s_cselect_b64 s[64:65], -1, 0
	s_mov_b32 s69, 0
	v_cmp_eq_u32_e64 s[40:41], 0, v4
	s_add_i32 s70, s14, 0xe000
	v_lshl_add_u64 v[130:131], s[94:95], 0, v[146:147]
	v_add_u32_e32 v140, 0, v5
	v_add_u32_e32 v141, 0, v6
	v_lshlrev_b32_e32 v146, 1, v2
	v_readlane_b32 s2, v255, 15
	v_readlane_b32 s12, v255, 17
	v_readlane_b32 s13, v254, 56
	v_readlane_b32 s21, v254, 54
	s_mov_b32 s53, 0x10000
	s_barrier
	s_branch .LBB0_577

.LBB0_853:
	s_add_u32 s37, s42, 0x51300000
	s_addc_u32 s40, s43, 0
	s_add_i32 s41, s13, 0x18000
	s_mov_b32 s66, s46
	s_mov_b32 s67, s47
	s_mov_b32 m0, s41
	v_readlane_b32 s12, v254, 15
	s_add_i32 s48, s13, 0x1a000
	s_add_i32 s49, s13, 0x8000
	s_add_i32 s68, s13, 0xa000
	s_nop 0
	buffer_load_dwordx4 v192, s[64:67], s12 offen lds
	s_mov_b32 m0, s48
	s_add_i32 s69, s13, 0x1c000
	buffer_load_dwordx4 v194, s[64:67], s12 offen lds
	s_mov_b32 m0, s49
	v_readlane_b32 s12, v254, 17
	s_add_i32 s72, s13, 0x1e000
	v_lshrrev_b32_e32 v4, 1, v2
	v_and_b32_e32 v4, 24, v4
	s_lshl_b32 s8, s8, 5
	v_and_b32_e32 v3, 15, v2
	buffer_load_dwordx4 v135, s[44:47], s12 offen lds
	s_mov_b32 m0, s68
	v_lshlrev_b32_e32 v5, 1, v4
	buffer_load_dwordx4 v193, s[44:47], s12 offen lds
	s_mov_b32 m0, s69
	v_readlane_b32 s12, v254, 19
	v_lshlrev_b32_e32 v2, 2, v2
	s_and_b32 s84, s8, 0x60
	s_lshl_b32 s73, s9, 6
	v_lshl_or_b32 v5, v3, 6, v5
	s_lshl_b32 s9, s9, 13
	buffer_load_dwordx4 v192, s[64:67], s12 offen lds
	s_mov_b32 m0, s72
	v_and_b32_e32 v2, 32, v2
	buffer_load_dwordx4 v194, s[64:67], s12 offen lds
	s_mov_b64 vcc, s[38:39]
	s_cbranch_vccz .Lgk_p1_2
	s_barrier
.Lgk_p1_2:
	s_waitcnt vmcnt(8)
	s_barrier
	s_lshl_b32 s8, s84, 7
	s_waitcnt vmcnt(6)
	s_add_i32 s85, s13, 0xc000
	s_or_b32 s14, s84, 0xfffff000
	v_bitop3_b32 v6, v5, s9, v2 bitop3:0xde
	v_bitop3_b32 v2, v5, s8, v2 bitop3:0xde
	s_cmpk_lt_u32 s2, 0x100
	v_lshlrev_b32_e32 v146, 3, v3
	s_mov_b64 s[92:93], s[42:43]
	s_cselect_b64 s[60:61], -1, 0
	v_lshl_or_b32 v134, v3, 11, v4
	s_add_i32 s15, s13, 0xe000
	v_lshl_add_u64 v[136:137], s[94:95], 0, v[146:147]
	s_mov_b32 s70, 0
	v_add_u32_e32 v195, 0, v2
	v_add_u32_e32 v196, 0, v6
	v_readlane_b32 s12, v254, 11
	v_readlane_b32 s16, v254, 13
	v_readlane_b32 s19, v254, 18
	v_readlane_b32 s18, v254, 16
	s_barrier
	s_branch .LBB0_856

.LBB0_875:
	s_add_u32 s86, s42, 0x4b300000
	s_addc_u32 s87, s43, 0
	s_add_u32 s40, s42, 0x4c300000
	v_writelane_b32 v255, s42, 55
	s_addc_u32 s41, s43, 0
	s_lshl_b32 s16, s89, 10
	s_lshl_b64 s[12:13], s[16:17], 2
	v_readlane_b32 s14, v252, 12
	v_readlane_b32 s15, v252, 13
	s_add_u32 s12, s14, s12
	s_addc_u32 s13, s15, s13
	s_add_i32 s24, s19, 0x18000
	s_mov_b32 m0, s24
	v_readlane_b32 s14, v254, 24
	s_add_i32 s25, s19, 0x1a000
	s_add_i32 s48, s19, 0x8000
	s_add_i32 s49, s19, 0xa000
	s_nop 0
	buffer_load_dwordx4 v229, s[44:47], s14 offen lds
	s_mov_b32 m0, s25
	s_add_i32 s64, s19, 0x1c000
	buffer_load_dwordx4 v231, s[44:47], s14 offen lds
	s_mov_b32 m0, s48
	v_readlane_b32 s14, v254, 26
	s_add_i32 s65, s19, 0x1e000
	v_and_b32_e32 v232, 15, v2
	v_lshrrev_b32_e32 v2, 1, v2
	v_and_b32_e32 v233, 24, v2
	s_lshl_b32 s8, s8, 5
	buffer_load_dwordx4 v228, s[60:63], s14 offen lds
	s_mov_b32 m0, s49
	v_lshlrev_b32_e32 v2, 1, v233
	buffer_load_dwordx4 v230, s[60:63], s14 offen lds
	s_mov_b32 m0, s64
	v_readlane_b32 s14, v254, 28
	s_and_b32 s67, s8, 0x60
	s_lshl_b32 s39, s9, 6
	v_lshl_or_b32 v3, v232, 6, v2
	s_lshl_b32 s9, s9, 13
	v_lshlrev_b32_e32 v2, 2, v232
	buffer_load_dwordx4 v229, s[44:47], s14 offen lds
	s_mov_b32 m0, s65
	s_lshl_b32 s8, s67, 7
	buffer_load_dwordx4 v231, s[44:47], s14 offen lds
	s_mov_b64 vcc, s[92:93]
	s_cbranch_vccz .Lgk_p1_3
	s_barrier
.Lgk_p1_3:
	s_waitcnt vmcnt(8)
	s_barrier
	s_add_i32 s72, s19, 0xc000
	v_and_b32_e32 v4, 32, v2
	s_cmpk_lt_u32 s2, 0x100
	v_writelane_b32 v255, s43, 56
	v_bitop3_b32 v5, v3, s9, v4 bitop3:0xde
	v_bitop3_b32 v6, v3, s8, v4 bitop3:0xde
	s_cselect_b64 s[8:9], -1, 0
	s_waitcnt vmcnt(6)
	v_writelane_b32 v255, s8, 44
	v_mul_u32_u24_e32 v3, 0xa000, v232
	v_or_b32_e32 v4, v233, v3
	v_writelane_b32 v255, s9, 45
	v_lshlrev_b32_e32 v146, 3, v233
	v_mov_b32_e32 v3, v147
	s_lshl_b32 s2, s67, 1
	s_add_i32 s73, s19, 0xe000
	v_lshl_add_u64 v[134:135], s[94:95], 0, v[146:147]
	v_lshl_add_u64 v[136:137], s[12:13], 0, v[2:3]
	s_mov_b32 s33, 0
	v_add_u32_e32 v234, 0, v6
	v_add_u32_e32 v235, 0, v5
	v_lshlrev_b32_e32 v138, 1, v4
	v_writelane_b32 v255, s2, 57
	v_readlane_b32 s84, v254, 20
	v_readlane_b32 s2, v254, 22
	v_readlane_b32 s13, v254, 27
	v_readlane_b32 s12, v254, 25
	s_barrier
	s_branch .LBB0_878

.LBB0_899:
	s_add_u32 s31, s42, 0x51300000
	s_addc_u32 s33, s43, 0
	s_add_i32 s36, s14, 0x18000
	s_mov_b32 m0, s36
	v_readlane_b32 s12, v255, 3
	s_add_i32 s37, s14, 0x1a000
	s_add_i32 s40, s14, 0x8000
	s_add_i32 s41, s14, 0xa000
	s_nop 0
	buffer_load_dwordx4 v175, s[60:63], s12 offen lds
	s_mov_b32 m0, s37
	s_add_i32 s48, s14, 0x1c000
	buffer_load_dwordx4 v177, s[60:63], s12 offen lds
	s_mov_b32 m0, s40
	v_readlane_b32 s12, v255, 5
	s_add_i32 s49, s14, 0x1e000
	v_lshrrev_b32_e32 v4, 1, v2
	v_and_b32_e32 v4, 24, v4
	s_lshl_b32 s8, s8, 5
	v_and_b32_e32 v3, 15, v2
	buffer_load_dwordx4 v174, s[44:47], s12 offen lds
	s_mov_b32 m0, s41
	v_lshlrev_b32_e32 v5, 1, v4
	buffer_load_dwordx4 v176, s[44:47], s12 offen lds
	s_mov_b32 m0, s48
	v_readlane_b32 s12, v255, 7
	v_lshlrev_b32_e32 v2, 2, v2
	s_and_b32 s67, s8, 0x60
	s_lshl_b32 s66, s9, 6
	v_lshl_or_b32 v5, v3, 6, v5
	s_lshl_b32 s9, s9, 13
	buffer_load_dwordx4 v175, s[60:63], s12 offen lds
	s_mov_b32 m0, s49
	v_and_b32_e32 v2, 32, v2
	buffer_load_dwordx4 v177, s[60:63], s12 offen lds
	s_mov_b64 vcc, s[38:39]
	s_cbranch_vccz .Lgk_p1_4
	s_barrier
.Lgk_p1_4:
	s_waitcnt vmcnt(8)
	s_barrier
	s_lshl_b32 s8, s67, 7
	s_waitcnt vmcnt(6)
	s_add_i32 s68, s14, 0xc000
	v_bitop3_b32 v6, v5, s9, v2 bitop3:0xde
	v_bitop3_b32 v5, v5, s8, v2 bitop3:0xde
	s_cmpk_lt_u32 s2, 0x100
	v_lshl_or_b32 v2, v3, 10, v4
	v_lshlrev_b32_e32 v146, 3, v3
	s_cselect_b64 s[64:65], -1, 0
	s_add_i32 s69, s14, 0xe000
	v_lshl_add_u64 v[130:131], s[94:95], 0, v[146:147]
	s_mov_b32 s70, 0
	v_add_u32_e32 v178, 0, v5
	v_add_u32_e32 v179, 0, v6
	v_lshlrev_b32_e32 v132, 1, v2
	v_readlane_b32 s2, v254, 63
	v_readlane_b32 s12, v255, 1
	v_readlane_b32 s21, v255, 6
	v_readlane_b32 s13, v255, 4
	v_readlane_b32 s52, v254, 61
	v_readlane_b32 s53, v254, 60
	s_barrier
	s_branch .LBB0_902

.LBB0_1187:
	s_add_i32 s34, s2, 0x18000
	s_or_b32 s14, s31, 0x80
	s_mov_b32 m0, s34
	s_add_i32 s35, s2, 0x1a000
	buffer_load_dwordx4 v134, s[64:67], s14 offen lds
	s_mov_b32 m0, s35
	s_or_b32 s22, s30, 0x80
	buffer_load_dwordx4 v136, s[64:67], s14 offen lds
	s_add_i32 s14, s2, 0x8000
	s_mov_b32 m0, s14
	s_add_i32 s36, s2, 0xa000
	buffer_load_dwordx4 v131, s[60:63], s22 offen lds
	s_mov_b32 m0, s36
	s_add_i32 s37, s2, 0x1c000
	buffer_load_dwordx4 v135, s[60:63], s22 offen lds
	s_or_b32 s22, s31, 0x200080
	s_mov_b32 m0, s37
	s_add_i32 s44, s2, 0x1e000
	buffer_load_dwordx4 v134, s[64:67], s22 offen lds
	s_mov_b32 m0, s44
	v_lshrrev_b32_e32 v3, 1, v2
	buffer_load_dwordx4 v136, s[64:67], s22 offen lds
	s_mov_b64 vcc, s[40:41]
	s_cbranch_vccz .Lgk_p1_5
	s_barrier
.Lgk_p1_5:
	s_waitcnt vmcnt(8)
	s_barrier
	v_and_b32_e32 v138, 24, v3
	s_lshl_b32 s9, s9, 5
	v_and_b32_e32 v137, 15, v2
	v_lshlrev_b32_e32 v3, 1, v138
	v_lshlrev_b32_e32 v2, 2, v2
	s_and_b32 s68, s9, 0x60
	s_lshl_b32 s45, s12, 6
	v_lshl_or_b32 v3, v137, 6, v3
	s_lshl_b32 s12, s12, 13
	v_and_b32_e32 v2, 32, v2
	s_lshl_b32 s9, s68, 7
	v_bitop3_b32 v4, v3, s12, v2 bitop3:0xde
	v_bitop3_b32 v2, v3, s9, v2 bitop3:0xde
	s_waitcnt vmcnt(6)
	s_add_i32 s69, s2, 0xc000
	v_mul_i32_i24_e32 v3, 0xfffff800, v137
	s_cmpk_lt_u32 s8, 0x100
	v_or_b32_e32 v132, v138, v3
	s_cselect_b64 s[42:43], -1, 0
	v_lshl_or_b32 v130, v137, 11, v138
	v_ashrrev_i32_e32 v133, 31, v132
	s_add_i32 s46, s2, 0xe000
	s_mov_b32 s47, 0
	v_add_u32_e32 v139, 0, v2
	v_add_u32_e32 v140, 0, v4
	s_barrier
	s_branch .LBB0_1190

.LBB0_1217:
	s_add_i32 s33, s16, 0x18000
	s_or_b32 s26, s22, 0x80
	s_mov_b32 m0, s33
	s_add_i32 s34, s16, 0x1a000
	buffer_load_dwordx4 v134, s[64:67], s26 offen lds
	s_mov_b32 m0, s34
	s_add_i32 s35, s16, 0x8000
	buffer_load_dwordx4 v136, s[64:67], s26 offen lds
	s_or_b32 s26, s19, 0x80
	s_mov_b32 m0, s35
	s_add_i32 s36, s16, 0xa000
	buffer_load_dwordx4 v131, s[60:63], s26 offen lds
	s_mov_b32 m0, s36
	s_add_i32 s37, s16, 0x1c000
	buffer_load_dwordx4 v135, s[60:63], s26 offen lds
	s_or_b32 s26, s22, 0x200080
	s_mov_b32 m0, s37
	s_add_i32 s68, s16, 0x1e000
	buffer_load_dwordx4 v134, s[64:67], s26 offen lds
	s_mov_b32 m0, s68
	v_lshrrev_b32_e32 v3, 1, v2
	buffer_load_dwordx4 v136, s[64:67], s26 offen lds
	s_mov_b64 vcc, s[40:41]
	s_cbranch_vccz .Lgk_p1_6
	s_barrier
.Lgk_p1_6:
	s_waitcnt vmcnt(8)
	s_barrier
	v_and_b32_e32 v138, 24, v3
	s_lshl_b32 s9, s9, 5
	v_and_b32_e32 v137, 15, v2
	v_lshlrev_b32_e32 v3, 1, v138
	v_lshlrev_b32_e32 v2, 2, v2
	s_and_b32 s70, s9, 0x60
	s_lshl_b32 s69, s14, 6
	v_lshl_or_b32 v3, v137, 6, v3
	s_lshl_b32 s14, s14, 13
	v_and_b32_e32 v2, 32, v2
	s_lshl_b32 s9, s70, 7
	v_bitop3_b32 v4, v3, s14, v2 bitop3:0xde
	v_bitop3_b32 v2, v3, s9, v2 bitop3:0xde
	s_waitcnt vmcnt(6)
	s_add_i32 s71, s16, 0xc000
	v_mul_i32_i24_e32 v3, 0xfffff800, v137
	s_cmpk_lt_u32 s8, 0x100
	v_or_b32_e32 v132, v138, v3
	s_cselect_b64 s[42:43], -1, 0
	v_lshl_or_b32 v130, v137, 11, v138
	v_ashrrev_i32_e32 v133, 31, v132
	s_add_i32 s72, s16, 0xe000
	s_mov_b32 s73, 0
	v_add_u32_e32 v139, 0, v2
	v_add_u32_e32 v140, 0, v4
	s_barrier
	s_branch .LBB0_1220

.LBB0_1247:
	s_add_i32 s34, s16, 0x18000
	s_or_b32 s14, s27, 0x80
	s_mov_b32 m0, s34
	s_add_i32 s35, s16, 0x1a000
	buffer_load_dwordx4 v134, s[68:71], s14 offen lds
	s_mov_b32 m0, s35
	s_or_b32 s22, s26, 0x80
	buffer_load_dwordx4 v136, s[68:71], s14 offen lds
	s_add_i32 s14, s16, 0x8000
	s_mov_b32 m0, s14
	s_add_i32 s36, s16, 0xa000
	buffer_load_dwordx4 v131, s[60:63], s22 offen lds
	s_mov_b32 m0, s36
	s_add_i32 s37, s16, 0x1c000
	buffer_load_dwordx4 v135, s[60:63], s22 offen lds
	s_or_b32 s22, s27, 0x80080
	s_mov_b32 m0, s37
	s_add_i32 s65, s16, 0x1e000
	buffer_load_dwordx4 v134, s[68:71], s22 offen lds
	s_mov_b32 m0, s65
	v_lshrrev_b32_e32 v3, 1, v2
	buffer_load_dwordx4 v136, s[68:71], s22 offen lds
	s_mov_b64 vcc, s[42:43]
	s_cbranch_vccz .Lgk_p1_7
	s_barrier
.Lgk_p1_7:
	s_waitcnt vmcnt(8)
	s_barrier
	v_and_b32_e32 v138, 24, v3
	s_lshl_b32 s9, s9, 5
	v_and_b32_e32 v137, 15, v2
	v_lshlrev_b32_e32 v3, 1, v138
	v_lshlrev_b32_e32 v2, 2, v2
	s_and_b32 s67, s9, 0x60
	s_lshl_b32 s66, s12, 6
	v_lshl_or_b32 v3, v137, 6, v3
	s_lshl_b32 s12, s12, 13
	v_and_b32_e32 v2, 32, v2
	s_lshl_b32 s9, s67, 7
	v_bitop3_b32 v4, v3, s12, v2 bitop3:0xde
	v_bitop3_b32 v2, v3, s9, v2 bitop3:0xde
	s_waitcnt vmcnt(6)
	s_add_i32 s72, s16, 0xc000
	v_mul_i32_i24_e32 v3, 0xfffff800, v137
	s_cmpk_lt_u32 s8, 0x100
	v_or_b32_e32 v132, v138, v3
	s_cselect_b64 s[44:45], -1, 0
	v_lshl_or_b32 v130, v137, 11, v138
	v_ashrrev_i32_e32 v133, 31, v132
	s_add_i32 s46, s16, 0xe000
	s_mov_b32 s47, 0
	v_add_u32_e32 v139, 0, v2
	v_add_u32_e32 v140, 0, v4
	s_barrier
	s_branch .LBB0_1250

.LBB0_1277:
	s_add_i32 s34, s2, 0x18000
	s_or_b32 s26, s22, 0x80
	s_mov_b32 m0, s34
	s_add_i32 s35, s2, 0x1a000
	buffer_load_dwordx4 v134, s[68:71], s26 offen lds
	s_mov_b32 m0, s35
	s_add_i32 s36, s2, 0x8000
	buffer_load_dwordx4 v136, s[68:71], s26 offen lds
	s_or_b32 s26, s19, 0x80
	s_mov_b32 m0, s36
	s_add_i32 s37, s2, 0xa000
	buffer_load_dwordx4 v131, s[60:63], s26 offen lds
	s_mov_b32 m0, s37
	s_add_i32 s65, s2, 0x1c000
	buffer_load_dwordx4 v135, s[60:63], s26 offen lds
	s_or_b32 s26, s22, 0x80080
	s_mov_b32 m0, s65
	s_add_i32 s66, s2, 0x1e000
	buffer_load_dwordx4 v134, s[68:71], s26 offen lds
	s_mov_b32 m0, s66
	v_lshrrev_b32_e32 v3, 1, v2
	buffer_load_dwordx4 v136, s[68:71], s26 offen lds
	s_mov_b64 vcc, s[42:43]
	s_cbranch_vccz .Lgk_p1_8
	s_barrier
.Lgk_p1_8:
	s_waitcnt vmcnt(8)
	s_barrier
	v_and_b32_e32 v138, 24, v3
	s_lshl_b32 s9, s9, 5
	v_and_b32_e32 v137, 15, v2
	v_lshlrev_b32_e32 v3, 1, v138
	v_lshlrev_b32_e32 v2, 2, v2
	s_and_b32 s72, s9, 0x60
	s_lshl_b32 s67, s14, 6
	v_lshl_or_b32 v3, v137, 6, v3
	s_lshl_b32 s14, s14, 13
	v_and_b32_e32 v2, 32, v2
	s_lshl_b32 s9, s72, 7
	v_bitop3_b32 v4, v3, s14, v2 bitop3:0xde
	v_bitop3_b32 v2, v3, s9, v2 bitop3:0xde
	s_waitcnt vmcnt(6)
	s_add_i32 s73, s2, 0xc000
	v_mul_i32_i24_e32 v3, 0xfffff800, v137
	s_cmpk_lt_u32 s8, 0x100
	v_or_b32_e32 v132, v138, v3
	s_cselect_b64 s[44:45], -1, 0
	v_lshl_or_b32 v130, v137, 11, v138
	v_ashrrev_i32_e32 v133, 31, v132
	s_add_i32 s82, s2, 0xe000
	s_mov_b32 s84, 0
	v_add_u32_e32 v139, 0, v2
	v_add_u32_e32 v140, 0, v4
	s_barrier
	s_branch .LBB0_1280

.LBB0_1583:
	s_lshl_b32 s12, s12, 5
	s_and_b32 s33, s12, 0x60
	s_lshl_b32 s31, s13, 6
	s_lshl_b32 s13, s13, 13
	s_lshl_b32 s12, s33, 7
	v_readlane_b32 s21, v255, 48
	s_add_u32 s34, s8, s21
	s_addc_u32 s35, s9, 0
	s_add_i32 s36, s14, 0x18000
	s_mov_b32 s46, s62
	s_mov_b32 s47, s63
	s_mov_b32 m0, s36
	v_readlane_b32 s8, v254, 31
	s_add_i32 s37, s14, 0x1a000
	s_add_i32 s66, s14, 0x8000
	s_add_i32 s67, s14, 0xa000
	s_nop 0
	buffer_load_dwordx4 v137, s[44:47], s8 offen lds
	s_mov_b32 m0, s37
	s_add_i32 s68, s14, 0x1c000
	buffer_load_dwordx4 v139, s[44:47], s8 offen lds
	s_mov_b32 m0, s66
	v_readlane_b32 s8, v254, 33
	s_add_i32 s69, s14, 0x1e000
	v_bfe_u32 v4, v2, 4, 2
	v_and_b32_e32 v3, 15, v2
	v_lshlrev_b32_e32 v5, 4, v4
	v_lshlrev_b32_e32 v2, 2, v2
	buffer_load_dwordx4 v136, s[60:63], s8 offen lds
	s_mov_b32 m0, s67
	v_lshl_or_b32 v5, v3, 6, v5
	buffer_load_dwordx4 v138, s[60:63], s8 offen lds
	s_mov_b32 m0, s68
	v_readlane_b32 s8, v254, 35
	v_and_b32_e32 v2, 32, v2
	v_bitop3_b32 v6, v5, s13, v2 bitop3:0xde
	v_bitop3_b32 v5, v5, s12, v2 bitop3:0xde
	s_add_i32 s70, s14, 0xc000
	v_lshlrev_b32_e32 v2, 11, v3
	buffer_load_dwordx4 v137, s[44:47], s8 offen lds
	s_mov_b32 m0, s69
	s_cmpk_lt_u32 s2, 0x100
	buffer_load_dwordx4 v139, s[44:47], s8 offen lds
	s_mov_b64 vcc, s[38:39]
	s_cbranch_vccz .Lgk_p1_9
	s_barrier
.Lgk_p1_9:
	s_waitcnt vmcnt(8)
	s_barrier
	s_waitcnt vmcnt(6)
	v_readlane_b32 s8, v255, 57
	v_lshl_or_b32 v2, v4, 3, v2
	v_lshlrev_b32_e32 v146, 3, v3
	v_readlane_b32 s9, v255, 58
	s_cselect_b64 s[64:65], -1, 0
	s_mov_b32 s71, 0
	v_cmp_eq_u32_e64 s[40:41], 0, v4
	s_add_i32 s72, s14, 0xe000
	v_lshl_add_u64 v[130:131], s[8:9], 0, v[146:147]
	v_add_u32_e32 v140, 0, v5
	v_add_u32_e32 v141, 0, v6
	v_lshlrev_b32_e32 v146, 1, v2
	v_readlane_b32 s2, v254, 36
	v_readlane_b32 s12, v254, 38
	v_readlane_b32 s21, v254, 34
	v_readlane_b32 s13, v254, 32
	s_mov_b32 s52, 0x10000
	s_barrier
	s_branch .LBB0_1586

.LBB0_1867:
	s_and_b32 s22, s18, 3
	s_lshl_b32 s46, s19, 6
	s_lshl_b32 s19, s19, 13
	s_lshl_b32 s26, s18, 5
	s_lshl_b32 s22, s22, 12
	s_add_u32 s25, s8, 0x47300000
	s_addc_u32 s30, s9, 0
	s_add_i32 s31, s2, 0x18000
	s_or_b32 s8, s94, 0x80
	s_mov_b32 s42, s62
	s_mov_b32 s43, s63
	s_mov_b32 m0, s31
	s_add_i32 s33, s2, 0x1a000
	buffer_load_dwordx4 v133, s[40:43], s8 offen lds
	s_mov_b32 m0, s33
	s_add_i32 s34, s2, 0x8000
	buffer_load_dwordx4 v135, s[40:43], s8 offen lds
	s_or_b32 s8, s95, 0x80
	s_mov_b32 m0, s34
	s_add_i32 s35, s2, 0xa000
	buffer_load_dwordx4 v132, s[60:63], s8 offen lds
	s_mov_b32 m0, s35
	s_add_i32 s36, s2, 0x1c000
	buffer_load_dwordx4 v134, s[60:63], s8 offen lds
	s_or_b32 s8, s94, 0x80080
	s_mov_b32 m0, s36
	s_add_i32 s37, s2, 0x1e000
	buffer_load_dwordx4 v133, s[40:43], s8 offen lds
	s_mov_b32 m0, s37
	s_add_i32 s72, s2, 0xc000
	buffer_load_dwordx4 v135, s[40:43], s8 offen lds
	s_mov_b64 vcc, s[44:45]
	s_cbranch_vccz .Lgk_p1_10
	s_barrier
.Lgk_p1_10:
	s_waitcnt vmcnt(8)
	s_barrier
	s_cmpk_lt_u32 s12, 0x100
	s_cselect_b64 s[64:65], -1, 0
	s_or_b32 s8, s46, 16
	s_ashr_i32 s9, s8, 31
	s_lshl_b64 s[68:69], s[8:9], 7
	s_or_b32 s8, s46, 32
	v_and_b32_e32 v3, 15, v2
	v_lshrrev_b32_e32 v4, 1, v2
	s_ashr_i32 s9, s8, 31
	v_and_b32_e32 v4, 24, v4
	v_lshlrev_b32_e32 v5, 6, v3
	v_lshlrev_b32_e32 v2, 2, v2
	s_lshl_b64 s[70:71], s[8:9], 7
	s_or_b32 s8, s46, 48
	v_lshl_or_b32 v6, v4, 1, v5
	v_and_b32_e32 v2, 32, v2
	s_ashr_i32 s47, s46, 31
	s_ashr_i32 s9, s8, 31
	v_bitop3_b32 v7, v6, s19, v2 bitop3:0xde
	s_bfe_u32 s73, s18, 0x10001
	s_and_b32 s19, s26, 32
	s_lshl_b64 s[66:67], s[46:47], 7
	s_add_i32 s47, s2, 0xe000
	s_lshl_b64 s[26:27], s[8:9], 7
	s_add_u32 s82, s66, 0x4000
	s_addc_u32 s84, s67, 0
	s_add_u32 s85, s66, 0x4800
	v_bitop3_b32 v6, v6, s22, v2 bitop3:0xde
	s_addc_u32 s22, s67, 0
	s_add_u32 s83, s66, 0x5000
	s_waitcnt vmcnt(6)
	s_addc_u32 s12, s67, 0
	v_readlane_b32 s8, v255, 57
	v_or_b32_e32 v2, v4, v5
	s_add_u32 s86, s66, 0x5800
	v_lshlrev_b32_e32 v146, 3, v3
	v_readlane_b32 s9, v255, 58
	s_addc_u32 s87, s67, 0
	s_mov_b32 s18, 0
	v_lshl_add_u64 v[130:131], s[8:9], 0, v[146:147]
	v_add_u32_e32 v136, 0, v6
	v_add_u32_e32 v137, 0, v7
	s_lshl_b32 s88, s19, 1
	v_lshlrev_b32_e32 v138, 1, v2
	s_barrier
	s_branch .LBB0_1870

.LBB0_2150:
	s_lshl_b32 s8, s8, 5
	s_and_b32 s35, s8, 0x60
	s_lshl_b32 s34, s9, 6
	s_lshl_b32 s9, s9, 13
	s_lshl_b32 s8, s35, 7
	v_readlane_b32 s12, v255, 48
	s_add_u32 s36, s38, s12
	s_addc_u32 s37, s39, 0
	s_add_i32 s68, s14, 0x18000
	s_mov_b32 s46, s62
	s_mov_b32 s47, s63
	s_mov_b32 m0, s68
	v_readlane_b32 s12, v254, 40
	s_add_i32 s69, s14, 0x1a000
	s_add_i32 s70, s14, 0x8000
	s_add_i32 s71, s14, 0xa000
	s_nop 0
	buffer_load_dwordx4 v137, s[44:47], s12 offen lds
	s_mov_b32 m0, s69
	s_add_i32 s72, s14, 0x1c000
	buffer_load_dwordx4 v139, s[44:47], s12 offen lds
	s_mov_b32 m0, s70
	v_readlane_b32 s12, v254, 42
	s_add_i32 s73, s14, 0x1e000
	v_bfe_u32 v4, v2, 4, 2
	v_and_b32_e32 v3, 15, v2
	v_lshlrev_b32_e32 v5, 4, v4
	v_lshlrev_b32_e32 v2, 2, v2
	buffer_load_dwordx4 v136, s[60:63], s12 offen lds
	s_mov_b32 m0, s71
	v_lshl_or_b32 v5, v3, 6, v5
	buffer_load_dwordx4 v138, s[60:63], s12 offen lds
	s_mov_b32 m0, s72
	v_readlane_b32 s12, v254, 44
	v_and_b32_e32 v2, 32, v2
	v_bitop3_b32 v6, v5, s9, v2 bitop3:0xde
	v_bitop3_b32 v5, v5, s8, v2 bitop3:0xde
	s_add_i32 s84, s14, 0xc000
	v_lshlrev_b32_e32 v2, 11, v3
	buffer_load_dwordx4 v137, s[44:47], s12 offen lds
	s_mov_b32 m0, s73
	s_cmpk_lt_u32 s2, 0x100
	buffer_load_dwordx4 v139, s[44:47], s12 offen lds
	s_mov_b64 vcc, s[64:65]
	s_cbranch_vccz .Lgk_p1_11
	s_barrier
.Lgk_p1_11:
	s_waitcnt vmcnt(8)
	s_barrier
	s_waitcnt vmcnt(6)
	v_lshl_or_b32 v2, v4, 3, v2
	v_lshlrev_b32_e32 v146, 3, v3
	s_cselect_b64 s[66:67], -1, 0
	s_mov_b32 s85, 0
	v_cmp_eq_u32_e64 s[40:41], 0, v4
	s_add_i32 s16, s14, 0xe000
	v_lshl_add_u64 v[130:131], s[92:93], 0, v[146:147]
	v_add_u32_e32 v140, 0, v5
	v_add_u32_e32 v141, 0, v6
	v_lshlrev_b32_e32 v146, 1, v2
	v_readlane_b32 s2, v254, 36
	v_readlane_b32 s12, v254, 38
	v_readlane_b32 s13, v254, 43
	v_readlane_b32 s21, v254, 41
	s_barrier
	s_branch .LBB0_2153

.LBB0_2168:
	s_ashr_i32 s23, s8, 31
	s_lshr_b32 s23, s23, 26
	s_lshl_b32 s25, s25, 5
	s_add_i32 s23, s8, s23
	s_and_b32 s25, s25, 0x60
	s_ashr_i32 s23, s23, 6
	s_lshl_b32 s24, s30, 6
	s_lshl_b32 s35, s30, 13
	s_lshl_b32 s40, s25, 7
	v_readlane_b32 s30, v255, 44
	s_add_u32 s30, s38, s30
	s_addc_u32 s31, s39, 0
	s_add_i32 s33, s13, 0x18000
	s_or_b32 s37, s82, 0x80
	s_mov_b32 s46, s62
	s_mov_b32 s47, s63
	s_mov_b32 m0, s33
	s_add_i32 s36, s13, 0x1a000
	buffer_load_dwordx4 v131, s[44:47], s37 offen lds
	s_mov_b32 m0, s36
	s_or_b32 s38, s73, 0x80
	buffer_load_dwordx4 v133, s[44:47], s37 offen lds
	s_add_i32 s37, s13, 0x8000
	s_mov_b32 m0, s37
	s_add_i32 s42, s13, 0xa000
	buffer_load_dwordx4 v130, s[60:63], s38 offen lds
	s_mov_b32 m0, s42
	s_add_i32 s43, s13, 0x1c000
	buffer_load_dwordx4 v132, s[60:63], s38 offen lds
	s_bitset1_b32 s34, 7
	s_mov_b32 m0, s43
	s_add_i32 s48, s13, 0x1e000
	buffer_load_dwordx4 v131, s[44:47], s34 offen lds
	s_mov_b32 m0, s48
	v_lshrrev_b32_e32 v4, 1, v2
	buffer_load_dwordx4 v133, s[44:47], s34 offen lds
	s_mov_b64 vcc, s[26:27]
	s_cbranch_vccz .Lgk_p1_12
	s_barrier
.Lgk_p1_12:
	s_waitcnt vmcnt(8)
	s_barrier
	v_and_b32_e32 v4, 24, v4
	v_and_b32_e32 v3, 15, v2
	v_lshlrev_b32_e32 v5, 1, v4
	v_lshlrev_b32_e32 v2, 2, v2
	v_lshl_or_b32 v5, v3, 6, v5
	v_and_b32_e32 v2, 32, v2
	s_cmp_gt_i32 s8, 63
	v_bitop3_b32 v6, v5, s35, v2 bitop3:0xde
	s_waitcnt vmcnt(6)
	s_cselect_b64 s[34:35], -1, 0
	s_add_i32 s49, s23, -2
	s_add_i32 s64, s13, 0xc000
	v_bitop3_b32 v5, v5, s40, v2 bitop3:0xde
	s_cmpk_lt_u32 s9, 0x100
	v_lshl_or_b32 v2, v3, 11, v4
	s_cselect_b64 s[38:39], -1, 0
	s_add_i32 s65, s13, 0xe000
	s_mov_b32 s66, 0
	v_add_u32_e32 v134, 0, v5
	v_add_u32_e32 v135, 0, v6
	v_lshlrev_b32_e32 v146, 1, v2
	v_readlane_b32 s71, v254, 36
	v_readlane_b32 s72, v254, 38
	s_barrier
	s_branch .LBB0_2171

.LBB0_2444:
	s_lshl_b32 s12, s12, 5
	s_and_b32 s33, s12, 0x60
	s_lshl_b32 s31, s13, 6
	s_lshl_b32 s13, s13, 13
	s_lshl_b32 s12, s33, 7
	v_readlane_b32 s21, v255, 44
	s_add_u32 s34, s8, s21
	s_addc_u32 s35, s9, 0
	s_add_i32 s36, s15, 0x18000
	s_mov_b32 s46, s62
	s_mov_b32 s47, s63
	s_mov_b32 m0, s36
	v_readlane_b32 s8, v255, 19
	s_add_i32 s37, s15, 0x1a000
	s_add_i32 s48, s15, 0x8000
	s_add_i32 s49, s15, 0xa000
	s_nop 0
	buffer_load_dwordx4 v185, s[44:47], s8 offen lds
	s_mov_b32 m0, s37
	s_add_i32 s66, s15, 0x1c000
	buffer_load_dwordx4 v187, s[44:47], s8 offen lds
	s_mov_b32 m0, s48
	v_readlane_b32 s8, v255, 21
	s_add_i32 s67, s15, 0x1e000
	v_bfe_u32 v4, v2, 4, 2
	v_and_b32_e32 v3, 15, v2
	v_lshlrev_b32_e32 v5, 4, v4
	v_lshlrev_b32_e32 v2, 2, v2
	buffer_load_dwordx4 v184, s[60:63], s8 offen lds
	s_mov_b32 m0, s49
	v_lshl_or_b32 v5, v3, 6, v5
	buffer_load_dwordx4 v186, s[60:63], s8 offen lds
	s_mov_b32 m0, s66
	v_readlane_b32 s8, v255, 23
	v_and_b32_e32 v2, 32, v2
	v_bitop3_b32 v6, v5, s13, v2 bitop3:0xde
	v_bitop3_b32 v7, v5, s12, v2 bitop3:0xde
	s_add_i32 s68, s15, 0xc000
	v_lshlrev_b32_e32 v2, 11, v3
	buffer_load_dwordx4 v185, s[44:47], s8 offen lds
	s_mov_b32 m0, s67
	v_lshlrev_b32_e32 v146, 3, v3
	buffer_load_dwordx4 v187, s[44:47], s8 offen lds
	s_mov_b64 vcc, s[42:43]
	s_cbranch_vccz .Lgk_p1_13
	s_barrier
.Lgk_p1_13:
	s_waitcnt vmcnt(8)
	s_barrier
	v_readlane_b32 s8, v252, 58
	s_waitcnt vmcnt(6)
	v_readlane_b32 s9, v252, 59
	s_cmpk_lt_u32 s2, 0x100
	v_lshl_or_b32 v2, v4, 3, v2
	v_cmp_eq_u32_e64 s[38:39], 0, v4
	v_lshl_add_u64 v[4:5], s[8:9], 0, v[146:147]
	s_mov_b64 s[8:9], 0x140000
	s_cselect_b64 s[64:65], -1, 0
	s_mov_b32 s69, 0
	s_add_i32 s70, s15, 0xe000
	v_lshl_add_u64 v[170:171], s[92:93], 0, v[146:147]
	v_lshl_add_u64 v[172:173], v[4:5], 0, s[8:9]
	v_add_u32_e32 v188, 0, v7
	v_add_u32_e32 v189, 0, v6
	v_lshlrev_b32_e32 v146, 1, v2
	v_readlane_b32 s2, v255, 15
	v_readlane_b32 s12, v255, 17
	v_readlane_b32 s21, v255, 22
	v_readlane_b32 s13, v255, 20
	s_barrier
	s_branch .LBB0_2447
